# plus P5 static re-deal of (head rank, q block) units across workgroups for forget-gate skip balance
# speedup vs baseline: 1.0154x; 1.0042x over previous
.LBB0_1282:
	s_andn2_b64 vcc, exec, s[0:1]
	s_cbranch_vccnz .LBB0_1369
	v_readlane_b32 s0, v255, 5
	v_readlane_b32 s1, v255, 6
	s_and_b64 vcc, exec, s[0:1]
	s_cbranch_vccnz .LBB0_1369
	s_ashr_i32 s0, s69, 6
	s_and_b32 s2, s69, 7
	s_sub_i32 s1, 23, s0
	s_cmp_lt_i32 s0, 8
	s_cselect_b32 s0, s0, s1
	s_lshl_b32 s0, s0, 2
	s_add_i32 s0, s0, 0
	s_add_i32 s0, s0, 0x12c40
	v_mov_b32_e32 v0, s0
	ds_read_b32 v168, v0
	s_lshl_b32 s0, s69, 5
	s_and_b32 s33, s0, 0x700
	s_lshl_b32 s0, s2, 11
	s_or_b32 s76, s33, s0
	s_lshl_b32 s0, s76, 12
	v_readlane_b32 s1, v254, 58
	s_add_u32 s3, s1, s0
	v_readlane_b32 s0, v254, 59
	s_addc_u32 s4, s0, 0
	s_waitcnt lgkmcnt(0)
	v_readfirstlane_b32 s0, v168
	s_lshl_b32 s0, s0, 7
	s_ashr_i32 s1, s0, 31
	s_lshl_b64 s[0:1], s[0:1], 1
	s_add_u32 s6, s3, s0
	s_addc_u32 s7, s4, s1
	s_lshl_b32 s2, s2, 23
	v_readlane_b32 s3, v254, 60
	s_add_u32 s3, s3, s2
	v_readlane_b32 s4, v254, 63
	s_addc_u32 s4, s4, 0
	s_add_u32 s64, s3, s0
	s_addc_u32 s65, s4, s1
	v_readlane_b32 s3, v255, 0
	s_add_u32 s2, s3, s2
	v_readlane_b32 s3, v254, 50
	s_addc_u32 s3, s3, 0
	s_add_u32 s70, s2, s0
	v_readlane_b32 s8, v254, 24
	s_addc_u32 s71, s3, s1
	s_and_b32 s0, s8, 0xffffffc0
	v_mbcnt_lo_u32_b32 v4, -1, 0
	v_mbcnt_hi_u32_b32 v4, -1, v4
	v_writelane_b32 v254, s0, 57
	v_add_u32_e32 v20, s0, v4
	s_movk_i32 s1, 0xffe0
	v_readfirstlane_b32 s0, v20
	s_ashr_i32 s0, s0, 1
	v_lshrrev_b32_e32 v2, 1, v4
	v_mov_b32_e32 v0, s0
	v_bfi_b32 v0, s1, v0, v4
	v_ashrrev_i32_e32 v1, 31, v0
	v_lshlrev_b64 v[0:1], 12, v[0:1]
	s_waitcnt vmcnt(0)
	v_mov_b32_e32 v96, 0
	v_writelane_b32 v254, s6, 54
	v_and_b32_e32 v2, 16, v2
	v_mov_b32_e32 v3, v96
	v_lshl_add_u64 v[0:1], s[6:7], 0, v[0:1]
	v_ashrrev_i32_e32 v21, 4, v20
	s_or_b32 s0, s33, 0xc0
	v_lshl_add_u64 v[8:9], v[0:1], 0, v[2:3]
	v_add_u32_e32 v0, s0, v21
	v_ashrrev_i32_e32 v1, 31, v0
	v_lshlrev_b32_e32 v22, 4, v4
	v_lshlrev_b64 v[12:13], 12, v[0:1]
	v_and_b32_e32 v10, 0xf0, v22
	v_lshl_add_u64 v[0:1], s[64:65], 0, v[12:13]
	v_mov_b32_e32 v11, v96
	v_add_u32_e32 v23, 32, v21
	v_lshl_add_u64 v[14:15], v[0:1], 0, v[10:11]
	v_add_u32_e32 v0, s0, v23
	v_ashrrev_i32_e32 v1, 31, v0
	v_lshlrev_b64 v[16:17], 12, v[0:1]
	s_or_b32 s1, s33, 0x80
	v_lshl_add_u64 v[0:1], s[64:65], 0, v[16:17]
	global_load_dwordx4 v[144:147], v[8:9], off
	global_load_dwordx4 v[136:139], v[8:9], off offset:32
	global_load_dwordx4 v[128:131], v[8:9], off offset:64
	global_load_dwordx4 v[124:127], v[8:9], off offset:96
	global_load_dwordx4 v[120:123], v[8:9], off offset:128
	global_load_dwordx4 v[116:119], v[8:9], off offset:160
	v_lshl_add_u64 v[18:19], v[0:1], 0, v[10:11]
	global_load_dwordx4 v[0:3], v[14:15], off
	global_load_dwordx4 v[4:7], v[18:19], off
	v_add_u32_e32 v14, s1, v21
	v_ashrrev_i32_e32 v15, 31, v14
	v_add_u32_e32 v18, s1, v23
	v_lshlrev_b64 v[14:15], 12, v[14:15]
	v_ashrrev_i32_e32 v19, 31, v18
	v_lshl_add_u64 v[14:15], s[64:65], 0, v[14:15]
	v_lshlrev_b64 v[18:19], 12, v[18:19]
	v_lshl_add_u64 v[14:15], v[14:15], 0, v[10:11]
	v_lshl_add_u64 v[18:19], s[64:65], 0, v[18:19]
	v_lshl_add_u64 v[12:13], s[70:71], 0, v[12:13]
	v_lshl_add_u64 v[18:19], v[18:19], 0, v[10:11]
	global_load_dwordx4 v[100:103], v[14:15], off
	global_load_dwordx4 v[104:107], v[18:19], off
	v_lshl_add_u64 v[12:13], v[12:13], 0, v[10:11]
	v_lshl_add_u64 v[14:15], s[70:71], 0, v[16:17]
	v_lshl_add_u64 v[10:11], v[14:15], 0, v[10:11]
	global_load_dwordx4 v[112:115], v[12:13], off
	global_load_dwordx4 v[108:111], v[10:11], off
	global_load_dwordx4 v[140:143], v[8:9], off offset:192
	global_load_dwordx4 v[132:135], v[8:9], off offset:224
	v_writelane_b32 v254, s7, 55
	s_movk_i32 s0, 0xf0
	v_bitop3_b32 v8, v22, v20, s0 bitop3:0x28
	v_readlane_b32 s0, v254, 16
	v_readlane_b32 s6, v254, 22
	v_readlane_b32 s1, v254, 17
	v_readlane_b32 s7, v254, 23
	s_add_u32 s0, s6, 0x300000
	s_addc_u32 s1, s7, 0
	v_writelane_b32 v255, s0, 9
	s_cmpk_lt_u32 s8, 0x100
	v_readlane_b32 s2, v254, 18
	v_writelane_b32 v255, s1, 10
	s_cselect_b64 s[0:1], -1, 0
	v_readlane_b32 s3, v254, 19
	v_readlane_b32 s4, v254, 20
	v_readlane_b32 s5, v254, 21
	v_writelane_b32 v254, s0, 0
	s_cmpk_gt_u32 s8, 0xff
	v_lshlrev_b32_e32 v9, 8, v21
	v_writelane_b32 v254, s1, 1
	s_cselect_b64 s[0:1], -1, 0
	v_writelane_b32 v254, s0, 42
	s_mov_b32 s73, 0
	v_add3_u32 v8, 0, v9, v8
	v_writelane_b32 v254, s1, 43
	s_add_i32 s0, 0, 0x12c80
	v_writelane_b32 v255, s0, 1
	v_mov_b32_e32 v169, 0xff800000
	s_mov_b32 s66, s69
	s_mov_b32 s67, 0
	s_waitcnt vmcnt(7)
	ds_write_b128 v8, v[0:3] offset:32768
	s_waitcnt vmcnt(6)
	ds_write_b128 v8, v[4:7] offset:40960
	s_waitcnt lgkmcnt(0)
	s_barrier
	s_branch .LBB0_1286

.LBB0_1286:
	s_add_i32 s4, s66, s68
	s_cmpk_lt_i32 s4, 0x200
	s_cselect_b64 s[2:3], -1, 0
	s_and_b64 s[0:1], s[2:3], exec
	s_cselect_b32 s6, s4, s66
	s_cmp_eq_u32 s67, 0
	s_cselect_b64 s[0:1], -1, 0
	s_and_b64 s[4:5], s[0:1], exec
	s_cselect_b32 s68, s66, s6
	s_or_b64 s[2:3], s[0:1], s[2:3]
	v_writelane_b32 v254, s2, 61
	v_mov_b32_e32 v170, v168
	s_mov_b32 s8, s33
	v_writelane_b32 v254, s3, 62
	s_xor_b64 s[2:3], s[2:3], -1
	v_writelane_b32 v255, s2, 17
	v_readlane_b32 s86, v254, 54
	s_and_b64 vcc, exec, s[2:3]
	v_writelane_b32 v255, s3, 18
	v_writelane_b32 v255, s76, 21
	s_mov_b64 s[90:91], s[70:71]
	s_mov_b64 s[88:89], s[64:65]
	v_readlane_b32 s87, v254, 55
	s_cbranch_vccnz .LBB0_1288
	s_and_b32 s4, s68, 7
	s_bfe_u32 s2, s68, 0x20006
	s_bfe_u32 s3, s68, 0x10008
	s_lshl_b32 s5, s3, 3
	s_or_b32 s2, s2, s5
	s_and_b64 s[6:7], s[0:1], exec
	s_cselect_b32 s6, 7, 0
	s_xor_b32 s2, s2, s6
	s_lshl_b32 s2, s2, 2
	s_add_i32 s2, s2, 0x12c40
	v_mov_b32_e32 v0, s2
	ds_read_b32 v170, v0
	s_lshl_b32 s5, s68, 5
	s_and_b32 s5, s5, 0x700
	s_lshl_b32 s3, s3, 10
	s_xor_b32 s5, s5, s3
	s_lshl_b32 s6, s6, 8
	s_xor_b32 s8, s5, s6
	s_lshl_b32 s2, s4, 11
	s_or_b32 s2, s8, s2
	v_writelane_b32 v255, s2, 21
	s_lshl_b32 s2, s2, 12
	v_readlane_b32 s3, v254, 58
	s_add_u32 s5, s3, s2
	v_readlane_b32 s2, v254, 59
	s_addc_u32 s6, s2, 0
	s_waitcnt lgkmcnt(0)
	v_readfirstlane_b32 s2, v170
	s_lshl_b32 s2, s2, 7
	s_ashr_i32 s3, s2, 31
	s_lshl_b64 s[2:3], s[2:3], 1
	s_add_u32 s86, s5, s2
	s_addc_u32 s87, s6, s3
	s_lshl_b32 s4, s4, 23
	v_readlane_b32 s5, v254, 60
	s_add_u32 s5, s5, s4
	v_readlane_b32 s6, v254, 63
	s_addc_u32 s6, s6, 0
	s_add_u32 s88, s5, s2
	s_addc_u32 s89, s6, s3
	v_readlane_b32 s5, v255, 0
	s_add_u32 s4, s5, s4
	v_readlane_b32 s5, v254, 50
	s_addc_u32 s5, s5, 0
	s_add_u32 s90, s4, s2
	s_addc_u32 s91, s5, s3
.LBB0_1288:
	s_andn2_b64 vcc, exec, s[0:1]
	s_lshl_b32 s0, s66, 4
	s_and_b32 s0, s0, 0x70
	v_add_u32_e32 v0, s0, v168
	v_ashrrev_i32_e32 v1, 31, v0
	v_readlane_b32 s0, v255, 9
	v_lshlrev_b64 v[0:1], 13, v[0:1]
	v_readlane_b32 s1, v255, 10
	v_mbcnt_lo_u32_b32 v6, -1, 0
	v_mbcnt_hi_u32_b32 v6, -1, v6
	s_nop 1
	v_lshl_add_u64 v[0:1], s[0:1], 0, v[0:1]
	v_readlane_b32 s0, v254, 57
	s_nop 1
	v_add_u32_e32 v7, s0, v6
	v_lshlrev_b32_e32 v4, 2, v7
	v_ashrrev_i32_e32 v5, 31, v4
	v_lshl_add_u64 v[0:1], v[4:5], 2, v[0:1]
	global_load_dwordx4 v[0:3], v[0:1], off
	v_and_b32_e32 v5, 63, v6
	v_cmp_ne_u32_e32 vcc, 0, v5
	v_lshlrev_b32_e32 v6, 2, v6
	s_waitcnt vmcnt(0)
	v_add_f32_e32 v1, v0, v1
	v_subbrev_co_u32_e64 v8, s[0:1], 0, v5, vcc
	v_add_f32_e32 v2, v2, v1
	v_lshlrev_b32_e32 v8, 2, v8
	v_add_f32_e32 v3, v3, v2
	ds_bpermute_b32 v8, v8, v3
	v_cmp_gt_u32_e64 s[0:1], 2, v5
	s_waitcnt lgkmcnt(0)
	v_add_f32_e32 v8, v3, v8
	v_cndmask_b32_e64 v9, -2, 0, s[0:1]
	v_add_lshl_u32 v9, v9, v5, 2
	v_cndmask_b32_e32 v8, v3, v8, vcc
	ds_bpermute_b32 v9, v9, v8
	v_cmp_gt_u32_e32 vcc, 4, v5
	s_waitcnt lgkmcnt(0)
	v_add_f32_e32 v9, v8, v9
	v_cndmask_b32_e64 v10, -4, 0, vcc
	v_add_lshl_u32 v10, v10, v5, 2
	v_cndmask_b32_e64 v8, v9, v8, s[0:1]
	ds_bpermute_b32 v9, v10, v8
	v_cmp_gt_u32_e64 s[0:1], 8, v5
	s_waitcnt lgkmcnt(0)
	v_add_f32_e32 v9, v8, v9
	v_cndmask_b32_e64 v10, -8, 0, s[0:1]
	v_add_lshl_u32 v10, v10, v5, 2
	v_cndmask_b32_e32 v8, v9, v8, vcc
	ds_bpermute_b32 v9, v10, v8
	v_cmp_gt_u32_e32 vcc, 16, v5
	s_waitcnt lgkmcnt(0)
	v_add_f32_e32 v9, v8, v9
	v_cndmask_b32_e64 v10, -16, 0, vcc
	v_add_lshl_u32 v10, v10, v5, 2
	v_cndmask_b32_e64 v8, v9, v8, s[0:1]
	ds_bpermute_b32 v9, v10, v8
	v_and_b32_e32 v10, 0x7c, v6
	s_waitcnt lgkmcnt(0)
	v_add_f32_e32 v6, v8, v9
	v_cndmask_b32_e32 v6, v6, v8, vcc
	ds_bpermute_b32 v9, v10, v6
	v_ashrrev_i32_e32 v8, 6, v7
	v_cmp_eq_u32_e32 vcc, 63, v5
	s_waitcnt lgkmcnt(0)
	v_add_f32_e32 v9, v6, v9
	s_and_saveexec_b64 s[0:1], vcc
	v_lshl_add_u32 v10, v8, 2, 0
	v_add_u32_e32 v10, 0x12c00, v10
	ds_write_b32 v10, v9
	s_or_b64 exec, exec, s[0:1]
	v_cmp_gt_u32_e32 vcc, 32, v5
	s_waitcnt lgkmcnt(0)
	s_barrier
	v_cndmask_b32_e32 v5, v9, v6, vcc
	v_sub_f32_e32 v6, v5, v3
	v_cmp_lt_i32_e32 vcc, 0, v8
	s_and_saveexec_b64 s[0:1], vcc
	s_cbranch_execz .LBB0_1301
	v_cmp_lt_u32_e32 vcc, 7, v8
	v_mov_b32_e32 v5, 0
	s_and_saveexec_b64 s[2:3], vcc
	s_cbranch_execz .LBB0_1296
	s_add_i32 s6, 0, 0x12c00
	v_and_b32_e32 v5, 0x7ffffff8, v8
	s_mov_b32 s7, 0
	s_mov_b64 s[4:5], 0
